# mlp2 GEMM layer 1: 1.5 tiles per workgroup via split-K of the shared tile (f32 partial tile through d_ws + flag hand-off), instead of 2 rounds with half the grid idle
# speedup vs baseline: 1.0202x; 1.0103x over previous
.LBB0_828:
	s_cmp_le_i32 s94, s4
	s_cselect_b64 s[0:1], -1, 0
	s_cmp_lt_i32 s4, s95
	s_cselect_b64 s[4:5], -1, 0
	s_and_b64 s[0:1], s[0:1], s[4:5]
	s_andn2_b64 vcc, exec, s[0:1]
	s_cbranch_vccnz .LBB0_150
	s_mov_b64 s[44:45], s[88:89]
	v_mov_b32_e32 v182, v194
	s_load_dwordx2 s[46:47], s[44:45], 0x90
	v_readfirstlane_b32 s42, v182
	s_waitcnt lgkmcnt(0)
	s_add_u32 s30, s46, 0x9000000
	s_addc_u32 s48, s47, 0
	s_and_b64 vcc, exec, s[40:41]
	s_ashr_i32 s40, s42, 6
	s_cbranch_vccnz .LBB0_841
	v_lshlrev_b32_e32 v0, 4, v182
	v_add_u32_e32 v1, 0x2000, v0
	v_ashrrev_i32_e32 v2, 31, v1
	v_lshrrev_b32_e32 v2, 22, v2
	v_add_u32_e32 v2, v1, v2
	s_waitcnt vmcnt(0)
	v_ashrrev_i32_e32 v8, 10, v2
	v_mul_i32_i24_e32 v2, 0x400, v8
	v_sub_u32_e32 v1, v1, v2
	v_lshrrev_b32_e32 v2, 4, v1
	v_bitop3_b32 v1, v2, v1, 32 bitop3:0x6c
	v_ashrrev_i32_e32 v2, 31, v1
	v_lshrrev_b32_e32 v2, 26, v2
	s_add_u32 s41, s46, 0x16000000
	s_mov_b32 s81, s31
	v_add_u32_e32 v2, v1, v2
	v_lshlrev_b32_e32 v3, 3, v8
	s_addc_u32 s43, s47, 0
	s_lshl_b64 s[0:1], s[80:81], 25
	v_ashrrev_i32_e32 v9, 6, v2
	v_and_b32_e32 v3, -16, v3
	s_add_u32 s49, s30, s0
	v_add_u32_e32 v3, v9, v3
	s_addc_u32 s50, s48, s1
	v_and_b32_e32 v4, 3, v9
	s_mov_b32 s1, 0x3ffe0
	v_lshrrev_b32_e32 v5, 2, v3
	v_lshlrev_b32_e32 v6, 1, v3
	v_and_b32_e32 v2, 0xc0, v2
	v_and_or_b32 v4, v3, s1, v4
	v_and_b32_e32 v5, 4, v5
	v_and_b32_e32 v6, 24, v6
	v_sub_u32_e32 v1, v1, v2
	v_or3_b32 v4, v4, v5, v6
	v_lshlrev_b32_e32 v5, 5, v8
	v_ashrrev_i16_sdwa v1, v196, sext(v1) dst_sel:DWORD dst_unused:UNUSED_PAD src0_sel:DWORD src1_sel:BYTE_0
	v_and_b32_e32 v5, 32, v5
	v_bfe_i32 v10, v1, 0, 16
	v_add_lshl_u32 v1, v5, v10, 1
	v_lshl_add_u32 v144, v4, 14, v1
	v_lshl_add_u32 v146, v3, 14, v1
	v_bfe_i32 v1, v182, 27, 1
	v_lshrrev_b32_e32 v1, 22, v1
	v_add_u32_e32 v1, v0, v1
	v_and_b32_e32 v1, 0xfffffc00, v1
	v_sub_u32_e32 v0, v0, v1
	v_lshrrev_b32_e32 v1, 4, v0
	v_ashrrev_i32_e32 v2, 31, v182
	v_bitop3_b32 v0, v1, v0, 32 bitop3:0x6c
	v_lshrrev_b32_e32 v2, 26, v2
	v_ashrrev_i32_e32 v1, 31, v0
	v_add_u32_e32 v2, v182, v2
	v_lshrrev_b32_e32 v1, 26, v1
	v_ashrrev_i32_e32 v12, 6, v2
	v_add_u32_e32 v1, v0, v1
	v_lshlrev_b32_e32 v2, 3, v12
	v_ashrrev_i32_e32 v11, 6, v1
	v_and_b32_e32 v2, -16, v2
	v_add_u32_e32 v2, v11, v2
	v_and_b32_e32 v3, 3, v11
	v_lshrrev_b32_e32 v4, 2, v2
	v_lshlrev_b32_e32 v5, 1, v2
	v_and_b32_e32 v1, 0xc0, v1
	v_and_or_b32 v3, v2, s1, v3
	v_and_b32_e32 v4, 4, v4
	v_and_b32_e32 v5, 24, v5
	v_sub_u32_e32 v0, v0, v1
	s_ashr_i32 s0, s42, 8
	s_lshl_b32 s51, s40, 10
	v_or3_b32 v3, v3, v4, v5
	v_lshlrev_b32_e32 v4, 5, v12
	v_ashrrev_i16_sdwa v0, v196, sext(v0) dst_sel:DWORD dst_unused:UNUSED_PAD src0_sel:DWORD src1_sel:BYTE_0
	s_cmp_eq_u32 s80, 1
	s_cselect_b32 s98, 1, 0
	s_cmp_eq_u32 s66, 0x100
	s_cselect_b32 s98, s98, 0
	v_readlane_b32 s100, v253, 19
	v_readlane_b32 s101, v253, 30
	s_cmp_lt_u32 s2, 0x80
	s_cselect_b32 s4, s98, 0
	s_cmp_eq_u32 s4, 0
	s_cbranch_scc1 .Lm2_first_done
	s_and_b32 s4, s2, 7
	s_mul_i32 s4, s4, 48
	s_lshr_b32 s5, s2, 3
	s_add_i32 s4, s4, s5
	s_add_i32 s4, s4, 32
	s_lshr_b32 s5, s4, 6
	s_and_b32 s4, s4, 63
	s_lshl_b32 s5, s5, 3
	s_and_b32 s101, s4, 7
	s_add_i32 s101, s101, s5
	s_lshr_b32 s100, s4, 3
.Lm2_first_done:
	s_lshl_b32 s4, s100, 22
	v_and_b32_e32 v4, 32, v4
	v_bfe_i32 v13, v0, 0, 16
	s_mov_b32 s5, 0
	s_add_u32 s22, s49, s4
	v_add_lshl_u32 v0, v4, v13, 1
	s_addc_u32 s23, s50, s5
	s_add_i32 s52, s51, 0
	v_lshl_add_u32 v152, v3, 14, v0
	s_add_i32 m0, s52, 0x10000
	s_lshl_b32 s4, s101, 22
	global_load_lds_dwordx4 v152, s[22:23]
	s_add_i32 m0, s52, 0x12000
	s_mov_b32 s5, 0
	s_add_u32 s20, s41, s4
	v_lshl_add_u32 v148, v2, 14, v0
	global_load_lds_dwordx4 v144, s[22:23]
	s_addc_u32 s21, s43, s5
	s_mov_b32 m0, s52
	s_add_i32 s53, s52, 0x2000
	global_load_lds_dwordx4 v148, s[20:21]
	s_mov_b32 m0, s53
	s_add_u32 s4, s22, 0x200000
	global_load_lds_dwordx4 v146, s[20:21]
	s_addc_u32 s5, s23, 0
	s_add_i32 m0, s52, 0x14000
	v_mov_b32_e32 v145, v153
	global_load_lds_dwordx4 v152, s[4:5]
	s_add_i32 m0, s52, 0x16000
	v_mov_b32_e32 v149, v153
	global_load_lds_dwordx4 v144, s[4:5]
	s_add_u32 s4, s20, 0x200000
	s_addc_u32 s5, s21, 0
	s_add_i32 s54, s52, 0x4000
	s_mov_b32 m0, s54
	s_add_i32 s55, s52, 0x6000
	global_load_lds_dwordx4 v148, s[4:5]
	s_mov_b32 m0, s55
	v_mov_b32_e32 v147, v153
	global_load_lds_dwordx4 v146, s[4:5]
	v_lshl_add_u64 v[6:7], s[22:23], 0, v[152:153]
	v_lshl_add_u64 v[4:5], s[22:23], 0, v[144:145]
	v_lshl_add_u64 v[2:3], s[20:21], 0, v[148:149]
	s_cmp_lg_u32 s0, 1
	v_lshl_add_u64 v[0:1], s[20:21], 0, v[146:147]
	s_cbranch_scc1 .LBB0_832
	s_barrier
.LBB0_832:
	v_lshrrev_b32_e32 v16, 1, v182
	s_add_u32 s56, s46, 0xd000000
	v_and_b32_e32 v16, 24, v16
	s_addc_u32 s57, s47, 0
	s_mul_i32 s1, s80, 0x24000
	v_and_b32_e32 v15, 15, v182
	v_lshlrev_b32_e32 v17, 1, v16
	s_add_u32 s58, s46, s1
	v_lshl_or_b32 v14, s0, 6, v15
	v_lshl_or_b32 v15, v15, 6, v17
	v_lshlrev_b32_e32 v17, 2, v182
	s_addc_u32 s59, s47, 0
	s_lshl_b32 s0, s0, 13
	v_and_b32_e32 v17, 32, v17
	v_bitop3_b32 v18, v15, s0, v17 bitop3:0xde
	s_lshl_b32 s0, s40, 5
	s_and_b32 s4, s0, 0x60
	s_add_i32 m0, s52, 0x18000
	v_lshl_add_u64 v[6:7], v[6:7], 0, s[18:19]
	s_lshl_b32 s0, s4, 7
	s_waitcnt vmcnt(4)
	s_barrier
	global_load_lds_dwordx4 v[6:7], off
	v_lshl_add_u64 v[4:5], v[4:5], 0, s[18:19]
	s_add_i32 m0, s52, 0x1a000
	s_add_i32 s60, s52, 0x8000
	s_add_i32 s61, s52, 0xa000
	v_bitop3_b32 v183, s0, v15, v17 bitop3:0xf6
	global_load_lds_dwordx4 v[4:5], off
	v_lshl_add_u64 v[2:3], v[2:3], 0, s[18:19]
	s_mov_b32 m0, s60
	s_add_u32 s0, s22, 0x200080
	global_load_lds_dwordx4 v[2:3], off
	v_lshl_add_u64 v[0:1], v[0:1], 0, s[18:19]
	s_mov_b32 m0, s61
	s_addc_u32 s1, s23, 0
	global_load_lds_dwordx4 v[0:1], off
	s_add_i32 m0, s52, 0x1c000
	v_lshl_add_u64 v[0:1], s[0:1], 0, v[152:153]
	global_load_lds_dwordx4 v[0:1], off
	v_lshl_add_u64 v[0:1], s[0:1], 0, v[144:145]
	s_add_i32 m0, s52, 0x1e000
	v_ashrrev_i32_e32 v15, 31, v14
	global_load_lds_dwordx4 v[0:1], off
	v_or_b32_e32 v0, 16, v14
	v_ashrrev_i32_e32 v1, 31, v0
	v_lshlrev_b64 v[170:171], 12, v[0:1]
	v_lshlrev_b32_e32 v0, 17, v12
	v_and_b32_e32 v0, 0xfffc0000, v0
	v_lshl_add_u32 v0, v11, 14, v0
	v_and_b32_e32 v1, 1, v12
	v_lshlrev_b64 v[150:151], 12, v[14:15]
	s_mov_b64 s[0:1], 0x80000
	v_lshl_or_b32 v0, v1, 6, v0
	v_lshl_add_u64 v[162:163], v[150:151], 0, s[0:1]
	s_mov_b64 s[0:1], 0x90000
	v_lshl_add_u32 v176, v13, 1, v0
	v_lshlrev_b32_e32 v0, 17, v8
	v_lshl_add_u64 v[164:165], v[150:151], 0, s[0:1]
	s_mov_b64 s[0:1], 0xa0000
	v_and_b32_e32 v0, 0xfffc0000, v0
	s_waitcnt vmcnt(6)
	v_or_b32_e32 v2, 32, v14
	v_or_b32_e32 v4, 48, v14
	v_lshl_add_u64 v[166:167], v[150:151], 0, s[0:1]
	s_mov_b64 s[0:1], 0xb0000
	v_lshl_add_u32 v0, v9, 14, v0
	v_and_b32_e32 v1, 1, v8
	v_ashrrev_i32_e32 v3, 31, v2
	v_ashrrev_i32_e32 v5, 31, v4
	v_lshl_add_u64 v[168:169], v[150:151], 0, s[0:1]
	v_lshl_or_b32 v0, v1, 6, v0
	s_mov_b32 s0, s101
	v_lshlrev_b64 v[172:173], 12, v[2:3]
	v_lshlrev_b64 v[174:175], 12, v[4:5]
	v_or_b32_e32 v184, s4, v16
	v_mov_b32_e32 v177, v153
	v_lshl_add_u32 v178, v10, 1, v0
	v_mov_b32_e32 v179, v153
	s_mov_b32 s62, 0
	v_add_u32_e32 v185, 0, v18
	s_mov_b32 s4, s100
	s_mov_b32 s5, s0
	s_barrier
	v_readlane_b32 s1, v253, 31
.LBB0_833:
	s_add_i32 s62, s62, 1
	s_mul_i32 s1, s62, s3
	s_mul_hi_u32 s6, s62, s66
	s_add_i32 s6, s6, s1
	s_mul_i32 s1, s62, s66
	s_add_u32 s14, s1, s2
	s_addc_u32 s15, s6, s33
	s_cmp_eq_u32 s98, 0
	s_cbranch_scc1 .Lm2_seq_done
	s_add_i32 s100, s2, 0x80
	s_cmp_lt_u32 s2, 0x80
	s_cselect_b32 s14, s2, s100
	s_cmp_eq_u32 s62, 1
	s_cselect_b32 s14, s14, 0x7fffffff
	s_mov_b32 s15, 0
.Lm2_seq_done:
	v_cmp_gt_i64_e64 s[38:39], s[14:15], v[158:159]
	s_and_b64 vcc, exec, s[38:39]
	s_cbranch_vccnz .LBB0_835
	s_ashr_i32 s0, s14, 31
	s_lshr_b32 s0, s0, 29
	s_add_i32 s0, s14, s0
	s_ashr_i32 s1, s0, 3
	s_and_b32 s0, s0, -8
	s_sub_i32 s0, s14, s0
	s_cmp_lt_i32 s0, 0
	s_cselect_b32 s6, 49, 48
	s_mul_i32 s0, s0, s6
	s_add_i32 s0, s0, s1
	s_ashr_i32 s1, s0, 31
	s_lshr_b32 s1, s1, 26
	s_add_i32 s1, s0, s1
	s_ashr_i32 s6, s1, 6
	s_lshl_b32 s6, s6, 3
	s_sub_i32 s7, 48, s6
	s_min_i32 s7, s7, 8
	s_abs_i32 s16, s7
	v_cvt_f32_u32_e32 v0, s16
	s_sub_i32 s24, 0, s16
	s_andn2_b32 s1, s1, 63
	s_sub_i32 s1, s0, s1
	v_rcp_iflag_f32_e32 v0, v0
	s_abs_i32 s0, s1
	s_xor_b32 s17, s1, s7
	s_ashr_i32 s17, s17, 31
	v_mul_f32_e32 v0, 0x4f7ffffe, v0
	v_cvt_u32_f32_e32 v0, v0
	s_nop 0
	v_readfirstlane_b32 s25, v0
	s_mul_i32 s24, s24, s25
	s_mul_hi_u32 s24, s25, s24
	s_add_i32 s25, s25, s24
	s_mul_hi_u32 s24, s0, s25
	s_mul_i32 s25, s24, s16
	s_sub_i32 s0, s0, s25
	s_add_i32 s34, s24, 1
	s_sub_i32 s25, s0, s16
	s_cmp_ge_u32 s0, s16
	s_cselect_b32 s24, s34, s24
	s_cselect_b32 s0, s25, s0
	s_add_i32 s25, s24, 1
	s_cmp_ge_u32 s0, s16
	s_cselect_b32 s0, s25, s24
	s_xor_b32 s0, s0, s17
	s_sub_i32 s0, s0, s17
	s_mul_i32 s7, s0, s7
	s_sub_i32 s1, s1, s7
	s_add_i32 s16, s6, s1
.LBB0_835:
	s_ashr_i32 s17, s16, 31
	s_lshl_b64 s[6:7], s[16:17], 22
	s_add_u32 s24, s41, s6
	v_cmp_lt_i64_e32 vcc, s[14:15], v[160:161]
	s_addc_u32 s25, s43, s7
	s_ashr_i32 s1, s0, 31
	s_lshl_b64 s[14:15], s[0:1], 22
	s_add_u32 s14, s49, s14
	s_addc_u32 s15, s50, s15
	s_cmp_ge_u32 s2, 0x80
	s_cselect_b32 s100, 0x2000, 0
	s_cmp_eq_u32 s62, 1
	s_cselect_b32 s100, s100, 0
	s_cmp_lg_u32 s98, 0
	s_cselect_b32 s100, s100, 0
	s_add_u32 s24, s24, s100
	s_addc_u32 s25, s25, 0
	s_add_u32 s14, s14, s100
	s_addc_u32 s15, s15, 0
	s_and_b64 s[6:7], vcc, exec
	s_cselect_b32 s6, s25, s21
	s_cselect_b32 s7, s24, s20
	s_and_b64 s[34:35], vcc, exec
	s_cselect_b32 s1, s15, s23
	s_cselect_b32 s17, s14, s22
	s_cmp_lt_u32 s2, 0x80
	s_cselect_b32 s99, 1, 2
	s_cmp_eq_u32 s62, s99
	s_cselect_b32 s99, s99, 0
	s_cmp_lg_u32 s98, 0
	s_cselect_b32 s99, s99, 0
	s_add_u32 s20, s20, 0x200080
	s_addc_u32 s21, s21, 0
	s_add_u32 s63, s22, 0x100
	v_mov_b32_e32 v0, 0
	s_addc_u32 s68, s23, 0
	s_cmp_lg_u32 s99, 0
	s_cselect_b32 s69, 62, -2
	v_mov_b32_e32 v1, v0
	v_mov_b32_e32 v2, v0
	v_mov_b32_e32 v3, v0
	v_mov_b32_e32 v4, v0
	v_mov_b32_e32 v5, v0
	v_mov_b32_e32 v6, v0
	v_mov_b32_e32 v7, v0
	v_mov_b32_e32 v12, v0
	v_mov_b32_e32 v13, v0
	v_mov_b32_e32 v14, v0
	v_mov_b32_e32 v15, v0
	v_mov_b32_e32 v20, v0
	v_mov_b32_e32 v21, v0
	v_mov_b32_e32 v22, v0
	v_mov_b32_e32 v23, v0
	v_mov_b32_e32 v28, v0
	v_mov_b32_e32 v29, v0
	v_mov_b32_e32 v30, v0
	v_mov_b32_e32 v31, v0
	v_mov_b32_e32 v36, v0
	v_mov_b32_e32 v37, v0
	v_mov_b32_e32 v38, v0
	v_mov_b32_e32 v39, v0
	v_mov_b32_e32 v44, v0
	v_mov_b32_e32 v45, v0
	v_mov_b32_e32 v46, v0
	v_mov_b32_e32 v47, v0
	v_mov_b32_e32 v52, v0
	v_mov_b32_e32 v53, v0
	v_mov_b32_e32 v54, v0
	v_mov_b32_e32 v55, v0
	v_mov_b32_e32 v8, v0
	v_mov_b32_e32 v9, v0
	v_mov_b32_e32 v10, v0
	v_mov_b32_e32 v11, v0
	v_mov_b32_e32 v16, v0
	v_mov_b32_e32 v17, v0
	v_mov_b32_e32 v18, v0
	v_mov_b32_e32 v19, v0
	v_mov_b32_e32 v24, v0
	v_mov_b32_e32 v25, v0
	v_mov_b32_e32 v26, v0
	v_mov_b32_e32 v27, v0
	v_mov_b32_e32 v32, v0
	v_mov_b32_e32 v33, v0
	v_mov_b32_e32 v34, v0
	v_mov_b32_e32 v35, v0
	v_mov_b32_e32 v40, v0
	v_mov_b32_e32 v41, v0
	v_mov_b32_e32 v42, v0
	v_mov_b32_e32 v43, v0
	v_mov_b32_e32 v48, v0
	v_mov_b32_e32 v49, v0
	v_mov_b32_e32 v50, v0
	v_mov_b32_e32 v51, v0
	v_mov_b32_e32 v56, v0
	v_mov_b32_e32 v57, v0
	v_mov_b32_e32 v58, v0
	v_mov_b32_e32 v59, v0
	v_mov_b32_e32 v60, v0
	v_mov_b32_e32 v61, v0
	v_mov_b32_e32 v62, v0
	v_mov_b32_e32 v63, v0
	v_mov_b32_e32 v64, v0
	v_mov_b32_e32 v65, v0
	v_mov_b32_e32 v66, v0
	v_mov_b32_e32 v67, v0
	v_mov_b32_e32 v68, v0
	v_mov_b32_e32 v69, v0
	v_mov_b32_e32 v70, v0
	v_mov_b32_e32 v71, v0
	v_mov_b32_e32 v76, v0
	v_mov_b32_e32 v77, v0
	v_mov_b32_e32 v78, v0
	v_mov_b32_e32 v79, v0
	v_mov_b32_e32 v84, v0
	v_mov_b32_e32 v85, v0
	v_mov_b32_e32 v86, v0
	v_mov_b32_e32 v87, v0
	v_mov_b32_e32 v92, v0
	v_mov_b32_e32 v93, v0
	v_mov_b32_e32 v94, v0
	v_mov_b32_e32 v95, v0
	v_mov_b32_e32 v100, v0
	v_mov_b32_e32 v101, v0
	v_mov_b32_e32 v102, v0
	v_mov_b32_e32 v103, v0
	v_mov_b32_e32 v108, v0
	v_mov_b32_e32 v109, v0
	v_mov_b32_e32 v110, v0
	v_mov_b32_e32 v111, v0
	v_mov_b32_e32 v116, v0
	v_mov_b32_e32 v117, v0
	v_mov_b32_e32 v118, v0
	v_mov_b32_e32 v119, v0
	v_mov_b32_e32 v72, v0
	v_mov_b32_e32 v73, v0
	v_mov_b32_e32 v74, v0
	v_mov_b32_e32 v75, v0
	v_mov_b32_e32 v80, v0
	v_mov_b32_e32 v81, v0
	v_mov_b32_e32 v82, v0
	v_mov_b32_e32 v83, v0
	v_mov_b32_e32 v88, v0
	v_mov_b32_e32 v89, v0
	v_mov_b32_e32 v90, v0
	v_mov_b32_e32 v91, v0
	v_mov_b32_e32 v96, v0
	v_mov_b32_e32 v97, v0
	v_mov_b32_e32 v98, v0
	v_mov_b32_e32 v99, v0
	v_mov_b32_e32 v104, v0
	v_mov_b32_e32 v105, v0
	v_mov_b32_e32 v106, v0
	v_mov_b32_e32 v107, v0
	v_mov_b32_e32 v112, v0
	v_mov_b32_e32 v113, v0
	v_mov_b32_e32 v114, v0
	v_mov_b32_e32 v115, v0
	v_mov_b32_e32 v128, v0
	v_mov_b32_e32 v129, v0
	v_mov_b32_e32 v130, v0
	v_mov_b32_e32 v131, v0
	v_mov_b32_e32 v140, v0
	v_mov_b32_e32 v141, v0
	v_mov_b32_e32 v142, v0
	v_mov_b32_e32 v143, v0
.LBB0_836:
	s_add_u32 s22, s20, 0xffe00080
	s_addc_u32 s23, s21, -1
	s_add_i32 s78, 0, 0x10000
	v_add_u32_e32 v136, s78, v183
	ds_read_b128 v[120:123], v136
	ds_read_b128 v[124:127], v136 offset:1024
	ds_read_b128 v[132:135], v136 offset:2048
	ds_read_b128 v[136:139], v136 offset:3072
	s_cmpk_eq_i32 s69, 0x7c
	s_cselect_b32 s35, s6, s23
	s_cselect_b32 s34, s7, s22
	s_cselect_b32 s23, s1, s68
	s_cselect_b32 s22, s17, s63
	v_lshl_add_u64 v[180:181], s[20:21], 0, v[176:177]
	s_add_i32 m0, s52, 0xc000
	ds_read_b128 v[186:189], v185
	ds_read_b128 v[190:193], v185 offset:1024
	ds_read_b128 v[206:209], v185 offset:2048
	ds_read_b128 v[210:213], v185 offset:3072
	ds_read_b128 v[214:217], v185 offset:4096
	ds_read_b128 v[218:221], v185 offset:5120
	ds_read_b128 v[222:225], v185 offset:6144
	ds_read_b128 v[226:229], v185 offset:7168
	global_load_lds_dwordx4 v[180:181], off
	v_lshl_add_u64 v[180:181], s[20:21], 0, v[178:179]
	s_add_i32 m0, s52, 0xe000
	s_nop 0
	global_load_lds_dwordx4 v[180:181], off
	s_waitcnt lgkmcnt(8)
	s_barrier
	s_waitcnt lgkmcnt(0)
	s_setprio 1
	s_waitcnt lgkmcnt(0)
	v_mfma_f32_16x16x32_bf16 v[140:143], v[120:123], v[186:189], v[140:143]
	v_mfma_f32_16x16x32_bf16 v[128:131], v[132:135], v[186:189], v[128:131]
	v_mfma_f32_16x16x32_bf16 v[112:115], v[120:123], v[206:209], v[112:115]
	v_mfma_f32_16x16x32_bf16 v[104:107], v[132:135], v[206:209], v[104:107]
	v_mfma_f32_16x16x32_bf16 v[96:99], v[120:123], v[214:217], v[96:99]
	v_mfma_f32_16x16x32_bf16 v[88:91], v[132:135], v[214:217], v[88:91]
	v_mfma_f32_16x16x32_bf16 v[80:83], v[120:123], v[222:225], v[80:83]
	v_mfma_f32_16x16x32_bf16 v[72:75], v[132:135], v[222:225], v[72:75]
	v_mfma_f32_16x16x32_bf16 v[140:143], v[124:127], v[190:193], v[140:143]
	v_mfma_f32_16x16x32_bf16 v[128:131], v[136:139], v[190:193], v[128:131]
	v_mfma_f32_16x16x32_bf16 v[112:115], v[124:127], v[210:213], v[112:115]
	v_mfma_f32_16x16x32_bf16 v[104:107], v[136:139], v[210:213], v[104:107]
	v_mfma_f32_16x16x32_bf16 v[96:99], v[124:127], v[218:221], v[96:99]
	v_mfma_f32_16x16x32_bf16 v[88:91], v[136:139], v[218:221], v[88:91]
	v_mfma_f32_16x16x32_bf16 v[80:83], v[124:127], v[226:229], v[80:83]
	v_mfma_f32_16x16x32_bf16 v[72:75], v[136:139], v[226:229], v[72:75]
	s_setprio 0
	s_barrier
	s_add_i32 s80, 0, 0x14000
	v_add_u32_e32 v180, s80, v183
	s_add_i32 s78, s78, s51
	ds_read_b128 v[230:233], v180
	ds_read_b128 v[234:237], v180 offset:1024
	ds_read_b128 v[238:241], v180 offset:2048
	ds_read_b128 v[242:245], v180 offset:3072
	v_lshl_add_u64 v[180:181], s[22:23], 0, v[152:153]
	s_mov_b32 m0, s78
	v_lshl_add_u64 v[246:247], s[22:23], 0, v[144:145]
	global_load_lds_dwordx4 v[180:181], off
	s_add_i32 m0, s78, 0x2000
	s_nop 0
	global_load_lds_dwordx4 v[246:247], off
	s_barrier
	s_waitcnt lgkmcnt(0)
	s_setprio 1
	s_waitcnt lgkmcnt(0)
	v_mfma_f32_16x16x32_bf16 v[116:119], v[230:233], v[186:189], v[116:119]
	v_mfma_f32_16x16x32_bf16 v[108:111], v[238:241], v[186:189], v[108:111]
	v_mfma_f32_16x16x32_bf16 v[100:103], v[230:233], v[206:209], v[100:103]
	v_mfma_f32_16x16x32_bf16 v[92:95], v[238:241], v[206:209], v[92:95]
	v_mfma_f32_16x16x32_bf16 v[84:87], v[230:233], v[214:217], v[84:87]
	v_mfma_f32_16x16x32_bf16 v[76:79], v[238:241], v[214:217], v[76:79]
	v_mfma_f32_16x16x32_bf16 v[68:71], v[230:233], v[222:225], v[68:71]
	v_mfma_f32_16x16x32_bf16 v[64:67], v[238:241], v[222:225], v[64:67]
	v_mfma_f32_16x16x32_bf16 v[116:119], v[234:237], v[190:193], v[116:119]
	v_mfma_f32_16x16x32_bf16 v[108:111], v[242:245], v[190:193], v[108:111]
	v_mfma_f32_16x16x32_bf16 v[100:103], v[234:237], v[210:213], v[100:103]
	v_mfma_f32_16x16x32_bf16 v[92:95], v[242:245], v[210:213], v[92:95]
	v_mfma_f32_16x16x32_bf16 v[84:87], v[234:237], v[218:221], v[84:87]
	v_mfma_f32_16x16x32_bf16 v[76:79], v[242:245], v[218:221], v[76:79]
	v_mfma_f32_16x16x32_bf16 v[68:71], v[234:237], v[226:229], v[68:71]
	v_mfma_f32_16x16x32_bf16 v[64:67], v[242:245], v[226:229], v[64:67]
	s_setprio 0
	s_mov_b32 m0, s52
	v_lshl_add_u64 v[248:249], s[34:35], 0, v[148:149]
	s_barrier
	ds_read_b128 v[186:189], v185 offset:16384
	ds_read_b128 v[190:193], v185 offset:17408
	ds_read_b128 v[206:209], v185 offset:18432
	ds_read_b128 v[210:213], v185 offset:19456
	ds_read_b128 v[214:217], v185 offset:20480
	ds_read_b128 v[218:221], v185 offset:21504
	ds_read_b128 v[222:225], v185 offset:22528
	ds_read_b128 v[226:229], v185 offset:23552
	global_load_lds_dwordx4 v[248:249], off
	v_lshl_add_u64 v[250:251], s[34:35], 0, v[146:147]
	s_mov_b32 m0, s53
	s_nop 0
	global_load_lds_dwordx4 v[250:251], off
	s_barrier
	s_waitcnt lgkmcnt(0)
	s_setprio 1
	s_waitcnt lgkmcnt(0)
	v_mfma_f32_16x16x32_bf16 v[60:63], v[120:123], v[186:189], v[60:63]
	v_mfma_f32_16x16x32_bf16 v[56:59], v[132:135], v[186:189], v[56:59]
	v_mfma_f32_16x16x32_bf16 v[48:51], v[120:123], v[206:209], v[48:51]
	v_mfma_f32_16x16x32_bf16 v[40:43], v[132:135], v[206:209], v[40:43]
	v_mfma_f32_16x16x32_bf16 v[32:35], v[120:123], v[214:217], v[32:35]
	v_mfma_f32_16x16x32_bf16 v[24:27], v[132:135], v[214:217], v[24:27]
	v_mfma_f32_16x16x32_bf16 v[16:19], v[120:123], v[222:225], v[16:19]
	v_mfma_f32_16x16x32_bf16 v[8:11], v[132:135], v[222:225], v[8:11]
	v_mfma_f32_16x16x32_bf16 v[60:63], v[124:127], v[190:193], v[60:63]
	v_mfma_f32_16x16x32_bf16 v[56:59], v[136:139], v[190:193], v[56:59]
	v_mfma_f32_16x16x32_bf16 v[48:51], v[124:127], v[210:213], v[48:51]
	v_mfma_f32_16x16x32_bf16 v[40:43], v[136:139], v[210:213], v[40:43]
	v_mfma_f32_16x16x32_bf16 v[32:35], v[124:127], v[218:221], v[32:35]
	v_mfma_f32_16x16x32_bf16 v[24:27], v[136:139], v[218:221], v[24:27]
	v_mfma_f32_16x16x32_bf16 v[16:19], v[124:127], v[226:229], v[16:19]
	v_mfma_f32_16x16x32_bf16 v[8:11], v[136:139], v[226:229], v[8:11]
	s_setprio 0
	s_barrier
	s_add_u32 s78, s22, 0x200000
	s_addc_u32 s79, s23, 0
	s_add_i32 s80, s80, s51
	v_lshl_add_u64 v[120:121], s[78:79], 0, v[152:153]
	s_mov_b32 m0, s80
	s_nop 0
	global_load_lds_dwordx4 v[120:121], off
	v_lshl_add_u64 v[120:121], s[78:79], 0, v[144:145]
	s_add_i32 m0, s80, 0x2000
	s_nop 0
	global_load_lds_dwordx4 v[120:121], off
	s_waitcnt vmcnt(6)
	s_barrier
	s_setprio 1
	v_mfma_f32_16x16x32_bf16 v[52:55], v[230:233], v[186:189], v[52:55]
	v_mfma_f32_16x16x32_bf16 v[44:47], v[238:241], v[186:189], v[44:47]
	v_mfma_f32_16x16x32_bf16 v[36:39], v[230:233], v[206:209], v[36:39]
	v_mfma_f32_16x16x32_bf16 v[28:31], v[238:241], v[206:209], v[28:31]
	v_mfma_f32_16x16x32_bf16 v[20:23], v[230:233], v[214:217], v[20:23]
	v_mfma_f32_16x16x32_bf16 v[12:15], v[238:241], v[214:217], v[12:15]
	v_mfma_f32_16x16x32_bf16 v[4:7], v[230:233], v[222:225], v[4:7]
	v_mfma_f32_16x16x32_bf16 v[0:3], v[238:241], v[222:225], v[0:3]
	v_mfma_f32_16x16x32_bf16 v[52:55], v[234:237], v[190:193], v[52:55]
	v_mfma_f32_16x16x32_bf16 v[44:47], v[242:245], v[190:193], v[44:47]
	v_mfma_f32_16x16x32_bf16 v[36:39], v[234:237], v[210:213], v[36:39]
	v_mfma_f32_16x16x32_bf16 v[28:31], v[242:245], v[210:213], v[28:31]
	v_mfma_f32_16x16x32_bf16 v[20:23], v[234:237], v[218:221], v[20:23]
	v_mfma_f32_16x16x32_bf16 v[12:15], v[242:245], v[218:221], v[12:15]
	v_mfma_f32_16x16x32_bf16 v[4:7], v[234:237], v[226:229], v[4:7]
	v_mfma_f32_16x16x32_bf16 v[0:3], v[242:245], v[226:229], v[0:3]
	s_setprio 0
	s_add_i32 s78, 0, 0x18000
	v_add_u32_e32 v136, s78, v183
	s_barrier
	ds_read_b128 v[120:123], v136
	ds_read_b128 v[124:127], v136 offset:1024
	ds_read_b128 v[132:135], v136 offset:2048
	ds_read_b128 v[136:139], v136 offset:3072
	s_add_u32 s34, s34, 0x200000
	s_addc_u32 s35, s35, 0
	s_mov_b32 m0, s54
	v_lshl_add_u64 v[230:231], s[34:35], 0, v[148:149]
	ds_read_b128 v[186:189], v185 offset:32768
	ds_read_b128 v[190:193], v185 offset:33792
	ds_read_b128 v[206:209], v185 offset:34816
	ds_read_b128 v[210:213], v185 offset:35840
	ds_read_b128 v[214:217], v185 offset:36864
	ds_read_b128 v[218:221], v185 offset:37888
	ds_read_b128 v[222:225], v185 offset:38912
	ds_read_b128 v[226:229], v185 offset:39936
	global_load_lds_dwordx4 v[230:231], off
	v_lshl_add_u64 v[230:231], s[34:35], 0, v[146:147]
	s_mov_b32 m0, s55
	s_nop 0
	global_load_lds_dwordx4 v[230:231], off
	s_waitcnt lgkmcnt(8)
	s_barrier
	s_waitcnt lgkmcnt(0)
	s_setprio 1
	s_waitcnt lgkmcnt(0)
	v_mfma_f32_16x16x32_bf16 v[140:143], v[120:123], v[186:189], v[140:143]
	v_mfma_f32_16x16x32_bf16 v[128:131], v[132:135], v[186:189], v[128:131]
	v_mfma_f32_16x16x32_bf16 v[112:115], v[120:123], v[206:209], v[112:115]
	v_mfma_f32_16x16x32_bf16 v[104:107], v[132:135], v[206:209], v[104:107]
	v_mfma_f32_16x16x32_bf16 v[96:99], v[120:123], v[214:217], v[96:99]
	v_mfma_f32_16x16x32_bf16 v[88:91], v[132:135], v[214:217], v[88:91]
	v_mfma_f32_16x16x32_bf16 v[80:83], v[120:123], v[222:225], v[80:83]
	v_mfma_f32_16x16x32_bf16 v[72:75], v[132:135], v[222:225], v[72:75]
	v_mfma_f32_16x16x32_bf16 v[140:143], v[124:127], v[190:193], v[140:143]
	v_mfma_f32_16x16x32_bf16 v[128:131], v[136:139], v[190:193], v[128:131]
	v_mfma_f32_16x16x32_bf16 v[112:115], v[124:127], v[210:213], v[112:115]
	v_mfma_f32_16x16x32_bf16 v[104:107], v[136:139], v[210:213], v[104:107]
	v_mfma_f32_16x16x32_bf16 v[96:99], v[124:127], v[218:221], v[96:99]
	v_mfma_f32_16x16x32_bf16 v[88:91], v[136:139], v[218:221], v[88:91]
	v_mfma_f32_16x16x32_bf16 v[80:83], v[124:127], v[226:229], v[80:83]
	v_mfma_f32_16x16x32_bf16 v[72:75], v[136:139], v[226:229], v[72:75]
	s_setprio 0
	s_barrier
	s_add_i32 s34, 0, 0x1c000
	s_add_i32 s35, s78, s51
	v_add_u32_e32 v205, s34, v183
	v_lshl_add_u64 v[180:181], v[180:181], 0, s[18:19]
	s_mov_b32 m0, s35
	ds_read_b128 v[230:233], v205
	ds_read_b128 v[234:237], v205 offset:1024
	ds_read_b128 v[238:241], v205 offset:2048
	ds_read_b128 v[242:245], v205 offset:3072
	global_load_lds_dwordx4 v[180:181], off
	v_lshl_add_u64 v[180:181], v[246:247], 0, s[18:19]
	s_add_i32 m0, s35, 0x2000
	s_nop 0
	global_load_lds_dwordx4 v[180:181], off
	s_barrier
	s_waitcnt lgkmcnt(0)
	s_setprio 1
	s_waitcnt lgkmcnt(0)
	v_mfma_f32_16x16x32_bf16 v[116:119], v[230:233], v[186:189], v[116:119]
	v_mfma_f32_16x16x32_bf16 v[108:111], v[238:241], v[186:189], v[108:111]
	v_mfma_f32_16x16x32_bf16 v[100:103], v[230:233], v[206:209], v[100:103]
	v_mfma_f32_16x16x32_bf16 v[92:95], v[238:241], v[206:209], v[92:95]
	v_mfma_f32_16x16x32_bf16 v[84:87], v[230:233], v[214:217], v[84:87]
	v_mfma_f32_16x16x32_bf16 v[76:79], v[238:241], v[214:217], v[76:79]
	v_mfma_f32_16x16x32_bf16 v[68:71], v[230:233], v[222:225], v[68:71]
	v_mfma_f32_16x16x32_bf16 v[64:67], v[238:241], v[222:225], v[64:67]
	v_mfma_f32_16x16x32_bf16 v[116:119], v[234:237], v[190:193], v[116:119]
	v_mfma_f32_16x16x32_bf16 v[108:111], v[242:245], v[190:193], v[108:111]
	v_mfma_f32_16x16x32_bf16 v[100:103], v[234:237], v[210:213], v[100:103]
	v_mfma_f32_16x16x32_bf16 v[92:95], v[242:245], v[210:213], v[92:95]
	v_mfma_f32_16x16x32_bf16 v[84:87], v[234:237], v[218:221], v[84:87]
	v_mfma_f32_16x16x32_bf16 v[76:79], v[242:245], v[218:221], v[76:79]
	v_mfma_f32_16x16x32_bf16 v[68:71], v[234:237], v[226:229], v[68:71]
	v_mfma_f32_16x16x32_bf16 v[64:67], v[242:245], v[226:229], v[64:67]
	s_setprio 0
	s_mov_b32 m0, s60
	v_lshl_add_u64 v[180:181], v[248:249], 0, s[18:19]
	s_barrier
	ds_read_b128 v[186:189], v185 offset:49152
	ds_read_b128 v[190:193], v185 offset:50176
	ds_read_b128 v[206:209], v185 offset:51200
	ds_read_b128 v[210:213], v185 offset:52224
	ds_read_b128 v[214:217], v185 offset:53248
	ds_read_b128 v[218:221], v185 offset:54272
	ds_read_b128 v[222:225], v185 offset:55296
	ds_read_b128 v[226:229], v185 offset:56320
	global_load_lds_dwordx4 v[180:181], off
	v_lshl_add_u64 v[180:181], v[250:251], 0, s[18:19]
	s_mov_b32 m0, s61
	s_nop 0
	global_load_lds_dwordx4 v[180:181], off
	s_barrier
	s_waitcnt lgkmcnt(0)
	s_setprio 1
	s_waitcnt lgkmcnt(0)
	v_mfma_f32_16x16x32_bf16 v[60:63], v[120:123], v[186:189], v[60:63]
	v_mfma_f32_16x16x32_bf16 v[56:59], v[132:135], v[186:189], v[56:59]
	v_mfma_f32_16x16x32_bf16 v[48:51], v[120:123], v[206:209], v[48:51]
	v_mfma_f32_16x16x32_bf16 v[40:43], v[132:135], v[206:209], v[40:43]
	v_mfma_f32_16x16x32_bf16 v[32:35], v[120:123], v[214:217], v[32:35]
	v_mfma_f32_16x16x32_bf16 v[24:27], v[132:135], v[214:217], v[24:27]
	v_mfma_f32_16x16x32_bf16 v[16:19], v[120:123], v[222:225], v[16:19]
	v_mfma_f32_16x16x32_bf16 v[8:11], v[132:135], v[222:225], v[8:11]
	v_mfma_f32_16x16x32_bf16 v[60:63], v[124:127], v[190:193], v[60:63]
	v_mfma_f32_16x16x32_bf16 v[56:59], v[136:139], v[190:193], v[56:59]
	v_mfma_f32_16x16x32_bf16 v[48:51], v[124:127], v[210:213], v[48:51]
	v_mfma_f32_16x16x32_bf16 v[40:43], v[136:139], v[210:213], v[40:43]
	v_mfma_f32_16x16x32_bf16 v[32:35], v[124:127], v[218:221], v[32:35]
	v_mfma_f32_16x16x32_bf16 v[24:27], v[136:139], v[218:221], v[24:27]
	v_mfma_f32_16x16x32_bf16 v[16:19], v[124:127], v[226:229], v[16:19]
	v_mfma_f32_16x16x32_bf16 v[8:11], v[136:139], v[226:229], v[8:11]
	s_setprio 0
	s_barrier
	s_add_u32 s22, s22, 0x200080
	s_addc_u32 s23, s23, 0
	s_add_i32 s34, s34, s51
	v_lshl_add_u64 v[120:121], s[22:23], 0, v[152:153]
	s_mov_b32 m0, s34
	s_nop 0
	global_load_lds_dwordx4 v[120:121], off
	v_lshl_add_u64 v[120:121], s[22:23], 0, v[144:145]
	s_add_i32 m0, s34, 0x2000
	s_nop 0
	global_load_lds_dwordx4 v[120:121], off
	s_waitcnt vmcnt(6)
	s_barrier
	s_setprio 1
	v_mfma_f32_16x16x32_bf16 v[52:55], v[230:233], v[186:189], v[52:55]
	v_mfma_f32_16x16x32_bf16 v[44:47], v[238:241], v[186:189], v[44:47]
	v_mfma_f32_16x16x32_bf16 v[36:39], v[230:233], v[206:209], v[36:39]
	v_mfma_f32_16x16x32_bf16 v[28:31], v[238:241], v[206:209], v[28:31]
	v_mfma_f32_16x16x32_bf16 v[20:23], v[230:233], v[214:217], v[20:23]
	v_mfma_f32_16x16x32_bf16 v[12:15], v[238:241], v[214:217], v[12:15]
	v_mfma_f32_16x16x32_bf16 v[4:7], v[230:233], v[222:225], v[4:7]
	v_mfma_f32_16x16x32_bf16 v[0:3], v[238:241], v[222:225], v[0:3]
	v_mfma_f32_16x16x32_bf16 v[52:55], v[234:237], v[190:193], v[52:55]
	v_mfma_f32_16x16x32_bf16 v[44:47], v[242:245], v[190:193], v[44:47]
	v_mfma_f32_16x16x32_bf16 v[36:39], v[234:237], v[210:213], v[36:39]
	v_mfma_f32_16x16x32_bf16 v[28:31], v[242:245], v[210:213], v[28:31]
	v_mfma_f32_16x16x32_bf16 v[20:23], v[234:237], v[218:221], v[20:23]
	v_mfma_f32_16x16x32_bf16 v[12:15], v[242:245], v[218:221], v[12:15]
	v_mfma_f32_16x16x32_bf16 v[4:7], v[234:237], v[226:229], v[4:7]
	v_mfma_f32_16x16x32_bf16 v[0:3], v[242:245], v[226:229], v[0:3]
	s_setprio 0
	s_add_i32 s69, s69, 2
	s_add_u32 s20, s20, 0x100
	s_addc_u32 s21, s21, 0
	s_add_u32 s63, s63, 0x100
	s_addc_u32 s68, s68, 0
	s_cmpk_gt_u32 s69, 0x7d
	s_barrier
	s_cbranch_scc0 .LBB0_836
	s_cmp_eq_u32 s99, 0
	s_cbranch_scc1 .Lm2_epi
	s_and_b32 s100, s2, 0x7f
	s_lshl_b32 s100, s100, 18
	s_add_u32 s100, s100, 0x29800000
	s_add_u32 s100, s46, s100
	s_addc_u32 s101, s47, 0
	v_lshlrev_b32_e32 v186, 4, v182
	s_cmp_eq_u32 s99, 1
	s_cbranch_scc1 .Lm2_put_partial
	s_and_b32 s6, s2, 0x7f
	s_lshl_b32 s6, s6, 6
	s_add_u32 s6, s6, 0x2970a000
	s_add_u32 s6, s46, s6
	s_addc_u32 s7, s47, 0
	v_mov_b32_e32 v187, 0
	s_mov_b32 s99, 0
.Lm2_spin:
	global_load_dword v188, v187, s[6:7] sc1
	s_waitcnt vmcnt(0)
	v_readfirstlane_b32 s1, v188
	s_nop 0
	s_cmp_ge_u32 s1, 8
	s_cbranch_scc1 .Lm2_spin_done
	s_sleep 2
	s_add_u32 s99, s99, 1
	s_cmp_lt_u32 s99, 0x4000
	s_cbranch_scc1 .Lm2_spin
.Lm2_spin_done:
	buffer_inv sc1
	s_waitcnt vmcnt(0)
	global_load_dwordx4 v[210:213], v186, s[100:101]
	s_add_u32 s100, s100, 0x2000
	s_addc_u32 s101, s101, 0
	global_load_dwordx4 v[214:217], v186, s[100:101]
	s_add_u32 s100, s100, 0x2000
	s_addc_u32 s101, s101, 0
	global_load_dwordx4 v[218:221], v186, s[100:101]
	s_add_u32 s100, s100, 0x2000
	s_addc_u32 s101, s101, 0
	global_load_dwordx4 v[222:225], v186, s[100:101]
	s_add_u32 s100, s100, 0x2000
	s_addc_u32 s101, s101, 0
	global_load_dwordx4 v[226:229], v186, s[100:101]
	s_add_u32 s100, s100, 0x2000
	s_addc_u32 s101, s101, 0
	global_load_dwordx4 v[230:233], v186, s[100:101]
	s_add_u32 s100, s100, 0x2000
	s_addc_u32 s101, s101, 0
	global_load_dwordx4 v[234:237], v186, s[100:101]
	s_add_u32 s100, s100, 0x2000
	s_addc_u32 s101, s101, 0
	global_load_dwordx4 v[238:241], v186, s[100:101]
	s_add_u32 s100, s100, 0x2000
	s_addc_u32 s101, s101, 0
	s_waitcnt vmcnt(7)
	v_pk_add_f32 v[140:141], v[140:141], v[210:211]
	v_pk_add_f32 v[142:143], v[142:143], v[212:213]
	s_waitcnt vmcnt(6)
	v_pk_add_f32 v[128:129], v[128:129], v[214:215]
	v_pk_add_f32 v[130:131], v[130:131], v[216:217]
	s_waitcnt vmcnt(5)
	v_pk_add_f32 v[116:117], v[116:117], v[218:219]
	v_pk_add_f32 v[118:119], v[118:119], v[220:221]
	s_waitcnt vmcnt(4)
	v_pk_add_f32 v[108:109], v[108:109], v[222:223]
	v_pk_add_f32 v[110:111], v[110:111], v[224:225]
	s_waitcnt vmcnt(3)
	v_pk_add_f32 v[112:113], v[112:113], v[226:227]
	v_pk_add_f32 v[114:115], v[114:115], v[228:229]
	s_waitcnt vmcnt(2)
	v_pk_add_f32 v[104:105], v[104:105], v[230:231]
	v_pk_add_f32 v[106:107], v[106:107], v[232:233]
	s_waitcnt vmcnt(1)
	v_pk_add_f32 v[100:101], v[100:101], v[234:235]
	v_pk_add_f32 v[102:103], v[102:103], v[236:237]
	s_waitcnt vmcnt(0)
	v_pk_add_f32 v[92:93], v[92:93], v[238:239]
	v_pk_add_f32 v[94:95], v[94:95], v[240:241]
	global_load_dwordx4 v[210:213], v186, s[100:101]
	s_add_u32 s100, s100, 0x2000
	s_addc_u32 s101, s101, 0
	global_load_dwordx4 v[214:217], v186, s[100:101]
	s_add_u32 s100, s100, 0x2000
	s_addc_u32 s101, s101, 0
	global_load_dwordx4 v[218:221], v186, s[100:101]
	s_add_u32 s100, s100, 0x2000
	s_addc_u32 s101, s101, 0
	global_load_dwordx4 v[222:225], v186, s[100:101]
	s_add_u32 s100, s100, 0x2000
	s_addc_u32 s101, s101, 0
	global_load_dwordx4 v[226:229], v186, s[100:101]
	s_add_u32 s100, s100, 0x2000
	s_addc_u32 s101, s101, 0
	global_load_dwordx4 v[230:233], v186, s[100:101]
	s_add_u32 s100, s100, 0x2000
	s_addc_u32 s101, s101, 0
	global_load_dwordx4 v[234:237], v186, s[100:101]
	s_add_u32 s100, s100, 0x2000
	s_addc_u32 s101, s101, 0
	global_load_dwordx4 v[238:241], v186, s[100:101]
	s_add_u32 s100, s100, 0x2000
	s_addc_u32 s101, s101, 0
	s_waitcnt vmcnt(7)
	v_pk_add_f32 v[96:97], v[96:97], v[210:211]
	v_pk_add_f32 v[98:99], v[98:99], v[212:213]
	s_waitcnt vmcnt(6)
	v_pk_add_f32 v[88:89], v[88:89], v[214:215]
	v_pk_add_f32 v[90:91], v[90:91], v[216:217]
	s_waitcnt vmcnt(5)
	v_pk_add_f32 v[84:85], v[84:85], v[218:219]
	v_pk_add_f32 v[86:87], v[86:87], v[220:221]
	s_waitcnt vmcnt(4)
	v_pk_add_f32 v[76:77], v[76:77], v[222:223]
	v_pk_add_f32 v[78:79], v[78:79], v[224:225]
	s_waitcnt vmcnt(3)
	v_pk_add_f32 v[80:81], v[80:81], v[226:227]
	v_pk_add_f32 v[82:83], v[82:83], v[228:229]
	s_waitcnt vmcnt(2)
	v_pk_add_f32 v[72:73], v[72:73], v[230:231]
	v_pk_add_f32 v[74:75], v[74:75], v[232:233]
	s_waitcnt vmcnt(1)
	v_pk_add_f32 v[68:69], v[68:69], v[234:235]
	v_pk_add_f32 v[70:71], v[70:71], v[236:237]
	s_waitcnt vmcnt(0)
	v_pk_add_f32 v[64:65], v[64:65], v[238:239]
	v_pk_add_f32 v[66:67], v[66:67], v[240:241]
	global_load_dwordx4 v[210:213], v186, s[100:101]
	s_add_u32 s100, s100, 0x2000
	s_addc_u32 s101, s101, 0
	global_load_dwordx4 v[214:217], v186, s[100:101]
	s_add_u32 s100, s100, 0x2000
	s_addc_u32 s101, s101, 0
	global_load_dwordx4 v[218:221], v186, s[100:101]
	s_add_u32 s100, s100, 0x2000
	s_addc_u32 s101, s101, 0
	global_load_dwordx4 v[222:225], v186, s[100:101]
	s_add_u32 s100, s100, 0x2000
	s_addc_u32 s101, s101, 0
	global_load_dwordx4 v[226:229], v186, s[100:101]
	s_add_u32 s100, s100, 0x2000
	s_addc_u32 s101, s101, 0
	global_load_dwordx4 v[230:233], v186, s[100:101]
	s_add_u32 s100, s100, 0x2000
	s_addc_u32 s101, s101, 0
	global_load_dwordx4 v[234:237], v186, s[100:101]
	s_add_u32 s100, s100, 0x2000
	s_addc_u32 s101, s101, 0
	global_load_dwordx4 v[238:241], v186, s[100:101]
	s_add_u32 s100, s100, 0x2000
	s_addc_u32 s101, s101, 0
	s_waitcnt vmcnt(7)
	v_pk_add_f32 v[60:61], v[60:61], v[210:211]
	v_pk_add_f32 v[62:63], v[62:63], v[212:213]
	s_waitcnt vmcnt(6)
	v_pk_add_f32 v[56:57], v[56:57], v[214:215]
	v_pk_add_f32 v[58:59], v[58:59], v[216:217]
	s_waitcnt vmcnt(5)
	v_pk_add_f32 v[52:53], v[52:53], v[218:219]
	v_pk_add_f32 v[54:55], v[54:55], v[220:221]
	s_waitcnt vmcnt(4)
	v_pk_add_f32 v[44:45], v[44:45], v[222:223]
	v_pk_add_f32 v[46:47], v[46:47], v[224:225]
	s_waitcnt vmcnt(3)
	v_pk_add_f32 v[48:49], v[48:49], v[226:227]
	v_pk_add_f32 v[50:51], v[50:51], v[228:229]
	s_waitcnt vmcnt(2)
	v_pk_add_f32 v[40:41], v[40:41], v[230:231]
	v_pk_add_f32 v[42:43], v[42:43], v[232:233]
	s_waitcnt vmcnt(1)
	v_pk_add_f32 v[36:37], v[36:37], v[234:235]
	v_pk_add_f32 v[38:39], v[38:39], v[236:237]
	s_waitcnt vmcnt(0)
	v_pk_add_f32 v[28:29], v[28:29], v[238:239]
	v_pk_add_f32 v[30:31], v[30:31], v[240:241]
	global_load_dwordx4 v[210:213], v186, s[100:101]
	s_add_u32 s100, s100, 0x2000
	s_addc_u32 s101, s101, 0
	global_load_dwordx4 v[214:217], v186, s[100:101]
	s_add_u32 s100, s100, 0x2000
	s_addc_u32 s101, s101, 0
	global_load_dwordx4 v[218:221], v186, s[100:101]
	s_add_u32 s100, s100, 0x2000
	s_addc_u32 s101, s101, 0
	global_load_dwordx4 v[222:225], v186, s[100:101]
	s_add_u32 s100, s100, 0x2000
	s_addc_u32 s101, s101, 0
	global_load_dwordx4 v[226:229], v186, s[100:101]
	s_add_u32 s100, s100, 0x2000
	s_addc_u32 s101, s101, 0
	global_load_dwordx4 v[230:233], v186, s[100:101]
	s_add_u32 s100, s100, 0x2000
	s_addc_u32 s101, s101, 0
	global_load_dwordx4 v[234:237], v186, s[100:101]
	s_add_u32 s100, s100, 0x2000
	s_addc_u32 s101, s101, 0
	global_load_dwordx4 v[238:241], v186, s[100:101]
	s_add_u32 s100, s100, 0x2000
	s_addc_u32 s101, s101, 0
	s_waitcnt vmcnt(7)
	v_pk_add_f32 v[32:33], v[32:33], v[210:211]
	v_pk_add_f32 v[34:35], v[34:35], v[212:213]
	s_waitcnt vmcnt(6)
	v_pk_add_f32 v[24:25], v[24:25], v[214:215]
	v_pk_add_f32 v[26:27], v[26:27], v[216:217]
	s_waitcnt vmcnt(5)
	v_pk_add_f32 v[20:21], v[20:21], v[218:219]
	v_pk_add_f32 v[22:23], v[22:23], v[220:221]
	s_waitcnt vmcnt(4)
	v_pk_add_f32 v[12:13], v[12:13], v[222:223]
	v_pk_add_f32 v[14:15], v[14:15], v[224:225]
	s_waitcnt vmcnt(3)
	v_pk_add_f32 v[16:17], v[16:17], v[226:227]
	v_pk_add_f32 v[18:19], v[18:19], v[228:229]
	s_waitcnt vmcnt(2)
	v_pk_add_f32 v[8:9], v[8:9], v[230:231]
	v_pk_add_f32 v[10:11], v[10:11], v[232:233]
	s_waitcnt vmcnt(1)
	v_pk_add_f32 v[4:5], v[4:5], v[234:235]
	v_pk_add_f32 v[6:7], v[6:7], v[236:237]
	s_waitcnt vmcnt(0)
	v_pk_add_f32 v[0:1], v[0:1], v[238:239]
	v_pk_add_f32 v[2:3], v[2:3], v[240:241]
	s_branch .Lm2_epi
.Lm2_put_partial:
	s_nop 7
	s_nop 7
	global_store_dwordx4 v186, v[140:143], s[100:101]
	s_add_u32 s100, s100, 0x2000
	s_addc_u32 s101, s101, 0
	global_store_dwordx4 v186, v[128:131], s[100:101]
	s_add_u32 s100, s100, 0x2000
	s_addc_u32 s101, s101, 0
	global_store_dwordx4 v186, v[116:119], s[100:101]
	s_add_u32 s100, s100, 0x2000
	s_addc_u32 s101, s101, 0
	global_store_dwordx4 v186, v[108:111], s[100:101]
	s_add_u32 s100, s100, 0x2000
	s_addc_u32 s101, s101, 0
	global_store_dwordx4 v186, v[112:115], s[100:101]
	s_add_u32 s100, s100, 0x2000
	s_addc_u32 s101, s101, 0
	global_store_dwordx4 v186, v[104:107], s[100:101]
	s_add_u32 s100, s100, 0x2000
	s_addc_u32 s101, s101, 0
	global_store_dwordx4 v186, v[100:103], s[100:101]
	s_add_u32 s100, s100, 0x2000
	s_addc_u32 s101, s101, 0
	global_store_dwordx4 v186, v[92:95], s[100:101]
	s_add_u32 s100, s100, 0x2000
	s_addc_u32 s101, s101, 0
	global_store_dwordx4 v186, v[96:99], s[100:101]
	s_add_u32 s100, s100, 0x2000
	s_addc_u32 s101, s101, 0
	global_store_dwordx4 v186, v[88:91], s[100:101]
	s_add_u32 s100, s100, 0x2000
	s_addc_u32 s101, s101, 0
	global_store_dwordx4 v186, v[84:87], s[100:101]
	s_add_u32 s100, s100, 0x2000
	s_addc_u32 s101, s101, 0
	global_store_dwordx4 v186, v[76:79], s[100:101]
	s_add_u32 s100, s100, 0x2000
	s_addc_u32 s101, s101, 0
	global_store_dwordx4 v186, v[80:83], s[100:101]
	s_add_u32 s100, s100, 0x2000
	s_addc_u32 s101, s101, 0
	global_store_dwordx4 v186, v[72:75], s[100:101]
	s_add_u32 s100, s100, 0x2000
	s_addc_u32 s101, s101, 0
	global_store_dwordx4 v186, v[68:71], s[100:101]
	s_add_u32 s100, s100, 0x2000
	s_addc_u32 s101, s101, 0
	global_store_dwordx4 v186, v[64:67], s[100:101]
	s_add_u32 s100, s100, 0x2000
	s_addc_u32 s101, s101, 0
	global_store_dwordx4 v186, v[60:63], s[100:101]
	s_add_u32 s100, s100, 0x2000
	s_addc_u32 s101, s101, 0
	global_store_dwordx4 v186, v[56:59], s[100:101]
	s_add_u32 s100, s100, 0x2000
	s_addc_u32 s101, s101, 0
	global_store_dwordx4 v186, v[52:55], s[100:101]
	s_add_u32 s100, s100, 0x2000
	s_addc_u32 s101, s101, 0
	global_store_dwordx4 v186, v[44:47], s[100:101]
	s_add_u32 s100, s100, 0x2000
	s_addc_u32 s101, s101, 0
	global_store_dwordx4 v186, v[48:51], s[100:101]
	s_add_u32 s100, s100, 0x2000
	s_addc_u32 s101, s101, 0
	global_store_dwordx4 v186, v[40:43], s[100:101]
	s_add_u32 s100, s100, 0x2000
	s_addc_u32 s101, s101, 0
	global_store_dwordx4 v186, v[36:39], s[100:101]
	s_add_u32 s100, s100, 0x2000
	s_addc_u32 s101, s101, 0
	global_store_dwordx4 v186, v[28:31], s[100:101]
	s_add_u32 s100, s100, 0x2000
	s_addc_u32 s101, s101, 0
	global_store_dwordx4 v186, v[32:35], s[100:101]
	s_add_u32 s100, s100, 0x2000
	s_addc_u32 s101, s101, 0
	global_store_dwordx4 v186, v[24:27], s[100:101]
	s_add_u32 s100, s100, 0x2000
	s_addc_u32 s101, s101, 0
	global_store_dwordx4 v186, v[20:23], s[100:101]
	s_add_u32 s100, s100, 0x2000
	s_addc_u32 s101, s101, 0
	global_store_dwordx4 v186, v[12:15], s[100:101]
	s_add_u32 s100, s100, 0x2000
	s_addc_u32 s101, s101, 0
	global_store_dwordx4 v186, v[16:19], s[100:101]
	s_add_u32 s100, s100, 0x2000
	s_addc_u32 s101, s101, 0
	global_store_dwordx4 v186, v[8:11], s[100:101]
	s_add_u32 s100, s100, 0x2000
	s_addc_u32 s101, s101, 0
	global_store_dwordx4 v186, v[4:7], s[100:101]
	s_add_u32 s100, s100, 0x2000
	s_addc_u32 s101, s101, 0
	global_store_dwordx4 v186, v[0:3], s[100:101]
	s_add_u32 s100, s100, 0x2000
	s_addc_u32 s101, s101, 0
	s_waitcnt vmcnt(0)
	buffer_wbl2 sc1
	s_waitcnt vmcnt(0)
	s_and_b32 s6, s2, 0x7f
	s_lshl_b32 s6, s6, 6
	s_add_u32 s6, s6, 0x2970a000
	s_add_u32 s6, s46, s6
	s_addc_u32 s7, s47, 0
	v_mov_b32_e32 v187, 0
	v_mov_b32_e32 v188, 1
	s_mov_b64 exec, 1
	global_atomic_add v187, v188, s[6:7]
	s_mov_b64 exec, -1
	s_branch .Lm2_epi_tail
.Lm2_epi:
	s_cmp_lt_i32 s5, 32
	s_cselect_b32 s1, 0x3000, s73
	s_cmp_lt_i32 s5, 16
	s_cselect_b32 s1, 0, s1
	s_lshl_b32 s1, s1, 2
	s_add_u32 s22, s58, s1
	s_addc_u32 s23, s59, 0
	v_lshl_or_b32 v120, s4, 8, v184
	s_mov_b32 s6, s5
	s_mov_b32 s7, 0
	s_lshl_b64 s[6:7], s[6:7], 20
	s_add_u32 s20, s56, s6
	s_addc_u32 s21, s57, s7
	v_ashrrev_i32_e32 v121, 31, v120
	v_lshlrev_b64 v[180:181], 1, v[120:121]
	v_lshl_add_u64 v[120:121], v[120:121], 2, s[22:23]
	s_mov_b64 s[6:7], 0x2850a000
	v_lshl_add_u64 v[188:189], v[120:121], 0, s[6:7]
	v_lshl_add_u64 v[180:181], s[20:21], 0, v[180:181]
	global_load_dwordx4 v[136:139], v[188:189], off
	global_load_dwordx4 v[132:135], v[188:189], off offset:16
	global_load_dwordx4 v[124:127], v[188:189], off offset:512
	global_load_dwordx4 v[120:123], v[188:189], off offset:528
	v_lshl_add_u64 v[186:187], v[150:151], 0, v[180:181]
	global_load_dwordx4 v[210:213], v[186:187], off
	global_load_dwordx4 v[214:217], v[186:187], off offset:256
	v_lshl_add_u64 v[186:187], v[170:171], 0, v[180:181]
	global_load_dwordx4 v[218:221], v[186:187], off
	global_load_dwordx4 v[222:225], v[186:187], off offset:256
	v_lshl_add_u64 v[186:187], v[172:173], 0, v[180:181]
	global_load_dwordx4 v[226:229], v[186:187], off
	global_load_dwordx4 v[230:233], v[186:187], off offset:256
	v_lshl_add_u64 v[186:187], v[174:175], 0, v[180:181]
	global_load_dwordx4 v[234:237], v[186:187], off
	global_load_dwordx4 v[238:241], v[186:187], off offset:256
	v_lshl_add_u64 v[186:187], v[162:163], 0, v[180:181]
	global_load_dwordx4 v[242:245], v[186:187], off
	global_load_dwordx4 v[246:249], v[186:187], off offset:256
	s_waitcnt vmcnt(9)
	v_lshlrev_b32_e32 v190, 16, v210
	v_and_b32_e32 v191, 0xffff0000, v210
	v_lshlrev_b32_e32 v192, 16, v211
	v_and_b32_e32 v193, 0xffff0000, v211
	v_lshlrev_b32_e32 v206, 16, v212
	v_and_b32_e32 v207, 0xffff0000, v212
	v_lshlrev_b32_e32 v208, 16, v213
	v_and_b32_e32 v209, 0xffff0000, v213
	v_lshl_add_u64 v[186:187], v[164:165], 0, v[180:181]
	global_load_dwordx4 v[210:213], v[186:187], off
	v_lshl_add_u64 v[188:189], v[150:151], 0, v[180:181]
	v_pk_fma_f32 v[140:141], v[140:141], v[136:137], v[190:191]
	v_pk_fma_f32 v[142:143], v[142:143], v[138:139], v[192:193]
	v_pk_fma_f32 v[128:129], v[128:129], v[132:133], v[206:207]
	v_pk_fma_f32 v[130:131], v[130:131], v[134:135], v[208:209]
	v_cvt_pk_bf16_f32 v140, v140, v141
	v_cvt_pk_bf16_f32 v141, v142, v143
	v_cvt_pk_bf16_f32 v142, v128, v129
	v_cvt_pk_bf16_f32 v143, v130, v131
	global_store_dwordx4 v[188:189], v[140:143], off
	s_waitcnt vmcnt(10)
	v_lshlrev_b32_e32 v190, 16, v214
	v_and_b32_e32 v191, 0xffff0000, v214
	v_lshlrev_b32_e32 v192, 16, v215
	v_and_b32_e32 v193, 0xffff0000, v215
	v_lshlrev_b32_e32 v206, 16, v216
	v_and_b32_e32 v207, 0xffff0000, v216
	v_lshlrev_b32_e32 v208, 16, v217
	v_and_b32_e32 v209, 0xffff0000, v217
	global_load_dwordx4 v[214:217], v[186:187], off offset:256
	v_pk_fma_f32 v[116:117], v[116:117], v[124:125], v[190:191]
	v_pk_fma_f32 v[118:119], v[118:119], v[126:127], v[192:193]
	v_pk_fma_f32 v[108:109], v[108:109], v[120:121], v[206:207]
	v_pk_fma_f32 v[110:111], v[110:111], v[122:123], v[208:209]
	v_cvt_pk_bf16_f32 v116, v116, v117
	v_cvt_pk_bf16_f32 v117, v118, v119
	v_cvt_pk_bf16_f32 v118, v108, v109
	v_cvt_pk_bf16_f32 v119, v110, v111
	global_store_dwordx4 v[188:189], v[116:119], off offset:256
	s_waitcnt vmcnt(11)
	v_lshlrev_b32_e32 v190, 16, v218
	v_and_b32_e32 v191, 0xffff0000, v218
	v_lshlrev_b32_e32 v192, 16, v219
	v_and_b32_e32 v193, 0xffff0000, v219
	v_lshlrev_b32_e32 v206, 16, v220
	v_and_b32_e32 v207, 0xffff0000, v220
	v_lshlrev_b32_e32 v208, 16, v221
	v_and_b32_e32 v209, 0xffff0000, v221
	v_lshl_add_u64 v[186:187], v[166:167], 0, v[180:181]
	global_load_dwordx4 v[218:221], v[186:187], off
	v_lshl_add_u64 v[250:251], v[170:171], 0, v[180:181]
	v_pk_fma_f32 v[112:113], v[112:113], v[136:137], v[190:191]
	v_pk_fma_f32 v[114:115], v[114:115], v[138:139], v[192:193]
	v_pk_fma_f32 v[104:105], v[104:105], v[132:133], v[206:207]
	v_pk_fma_f32 v[106:107], v[106:107], v[134:135], v[208:209]
	v_cvt_pk_bf16_f32 v112, v112, v113
	v_cvt_pk_bf16_f32 v113, v114, v115
	v_cvt_pk_bf16_f32 v114, v104, v105
	v_cvt_pk_bf16_f32 v115, v106, v107
	global_store_dwordx4 v[250:251], v[112:115], off
	s_waitcnt vmcnt(12)
	v_lshlrev_b32_e32 v190, 16, v222
	v_and_b32_e32 v191, 0xffff0000, v222
	v_lshlrev_b32_e32 v192, 16, v223
	v_and_b32_e32 v193, 0xffff0000, v223
	v_lshlrev_b32_e32 v206, 16, v224
	v_and_b32_e32 v207, 0xffff0000, v224
	v_lshlrev_b32_e32 v208, 16, v225
	v_and_b32_e32 v209, 0xffff0000, v225
	global_load_dwordx4 v[222:225], v[186:187], off offset:256
	v_pk_fma_f32 v[100:101], v[100:101], v[124:125], v[190:191]
	v_pk_fma_f32 v[102:103], v[102:103], v[126:127], v[192:193]
	v_pk_fma_f32 v[92:93], v[92:93], v[120:121], v[206:207]
	v_pk_fma_f32 v[94:95], v[94:95], v[122:123], v[208:209]
	v_cvt_pk_bf16_f32 v100, v100, v101
	v_cvt_pk_bf16_f32 v101, v102, v103
	v_cvt_pk_bf16_f32 v102, v92, v93
	v_cvt_pk_bf16_f32 v103, v94, v95
	global_store_dwordx4 v[250:251], v[100:103], off offset:256
	s_waitcnt vmcnt(13)
	v_lshlrev_b32_e32 v190, 16, v226
	v_and_b32_e32 v191, 0xffff0000, v226
	v_lshlrev_b32_e32 v192, 16, v227
	v_and_b32_e32 v193, 0xffff0000, v227
	v_lshlrev_b32_e32 v206, 16, v228
	v_and_b32_e32 v207, 0xffff0000, v228
	v_lshlrev_b32_e32 v208, 16, v229
	v_and_b32_e32 v209, 0xffff0000, v229
	v_lshl_add_u64 v[186:187], v[168:169], 0, v[180:181]
	global_load_dwordx4 v[226:229], v[186:187], off
	v_lshl_add_u64 v[188:189], v[172:173], 0, v[180:181]
	v_pk_fma_f32 v[96:97], v[96:97], v[136:137], v[190:191]
	v_pk_fma_f32 v[98:99], v[98:99], v[138:139], v[192:193]
	v_pk_fma_f32 v[88:89], v[88:89], v[132:133], v[206:207]
	v_pk_fma_f32 v[90:91], v[90:91], v[134:135], v[208:209]
	v_cvt_pk_bf16_f32 v96, v96, v97
	v_cvt_pk_bf16_f32 v97, v98, v99
	v_cvt_pk_bf16_f32 v98, v88, v89
	v_cvt_pk_bf16_f32 v99, v90, v91
	global_store_dwordx4 v[188:189], v[96:99], off
	s_waitcnt vmcnt(14)
	v_lshlrev_b32_e32 v190, 16, v230
	v_and_b32_e32 v191, 0xffff0000, v230
	v_lshlrev_b32_e32 v192, 16, v231
	v_and_b32_e32 v193, 0xffff0000, v231
	v_lshlrev_b32_e32 v206, 16, v232
	v_and_b32_e32 v207, 0xffff0000, v232
	v_lshlrev_b32_e32 v208, 16, v233
	v_and_b32_e32 v209, 0xffff0000, v233
	global_load_dwordx4 v[230:233], v[186:187], off offset:256
	v_pk_fma_f32 v[84:85], v[84:85], v[124:125], v[190:191]
	v_pk_fma_f32 v[86:87], v[86:87], v[126:127], v[192:193]
	v_pk_fma_f32 v[76:77], v[76:77], v[120:121], v[206:207]
	v_pk_fma_f32 v[78:79], v[78:79], v[122:123], v[208:209]
	v_cvt_pk_bf16_f32 v84, v84, v85
	v_cvt_pk_bf16_f32 v85, v86, v87
	v_cvt_pk_bf16_f32 v86, v76, v77
	v_cvt_pk_bf16_f32 v87, v78, v79
	global_store_dwordx4 v[188:189], v[84:87], off offset:256
	s_waitcnt vmcnt(15)
	v_lshlrev_b32_e32 v190, 16, v234
	v_and_b32_e32 v191, 0xffff0000, v234
	v_lshlrev_b32_e32 v192, 16, v235
	v_and_b32_e32 v193, 0xffff0000, v235
	v_lshlrev_b32_e32 v206, 16, v236
	v_and_b32_e32 v207, 0xffff0000, v236
	v_lshlrev_b32_e32 v208, 16, v237
	v_and_b32_e32 v209, 0xffff0000, v237
	v_lshl_add_u64 v[250:251], v[174:175], 0, v[180:181]
	v_pk_fma_f32 v[80:81], v[80:81], v[136:137], v[190:191]
	v_pk_fma_f32 v[82:83], v[82:83], v[138:139], v[192:193]
	v_pk_fma_f32 v[72:73], v[72:73], v[132:133], v[206:207]
	v_pk_fma_f32 v[74:75], v[74:75], v[134:135], v[208:209]
	v_cvt_pk_bf16_f32 v80, v80, v81
	v_cvt_pk_bf16_f32 v81, v82, v83
	v_cvt_pk_bf16_f32 v82, v72, v73
	v_cvt_pk_bf16_f32 v83, v74, v75
	global_store_dwordx4 v[250:251], v[80:83], off
	s_waitcnt vmcnt(15)
	v_lshlrev_b32_e32 v190, 16, v238
	v_and_b32_e32 v191, 0xffff0000, v238
	v_lshlrev_b32_e32 v192, 16, v239
	v_and_b32_e32 v193, 0xffff0000, v239
	v_lshlrev_b32_e32 v206, 16, v240
	v_and_b32_e32 v207, 0xffff0000, v240
	v_lshlrev_b32_e32 v208, 16, v241
	v_and_b32_e32 v209, 0xffff0000, v241
	v_pk_fma_f32 v[68:69], v[68:69], v[124:125], v[190:191]
	v_pk_fma_f32 v[70:71], v[70:71], v[126:127], v[192:193]
	v_pk_fma_f32 v[64:65], v[64:65], v[120:121], v[206:207]
	v_pk_fma_f32 v[66:67], v[66:67], v[122:123], v[208:209]
	v_cvt_pk_bf16_f32 v68, v68, v69
	v_cvt_pk_bf16_f32 v69, v70, v71
	v_cvt_pk_bf16_f32 v70, v64, v65
	v_cvt_pk_bf16_f32 v71, v66, v67
	global_store_dwordx4 v[250:251], v[68:71], off offset:256
	s_waitcnt vmcnt(15)
	v_lshlrev_b32_e32 v190, 16, v242
	v_and_b32_e32 v191, 0xffff0000, v242
	v_lshlrev_b32_e32 v192, 16, v243
	v_and_b32_e32 v193, 0xffff0000, v243
	v_lshlrev_b32_e32 v206, 16, v244
	v_and_b32_e32 v207, 0xffff0000, v244
	v_lshlrev_b32_e32 v208, 16, v245
	v_and_b32_e32 v209, 0xffff0000, v245
	v_lshl_add_u64 v[188:189], v[162:163], 0, v[180:181]
	v_pk_fma_f32 v[60:61], v[60:61], v[136:137], v[190:191]
	v_pk_fma_f32 v[62:63], v[62:63], v[138:139], v[192:193]
	v_pk_fma_f32 v[56:57], v[56:57], v[132:133], v[206:207]
	v_pk_fma_f32 v[58:59], v[58:59], v[134:135], v[208:209]
	v_cvt_pk_bf16_f32 v60, v60, v61
	v_cvt_pk_bf16_f32 v61, v62, v63
	v_cvt_pk_bf16_f32 v62, v56, v57
	v_cvt_pk_bf16_f32 v63, v58, v59
	global_store_dwordx4 v[188:189], v[60:63], off
	s_waitcnt vmcnt(15)
	v_lshlrev_b32_e32 v190, 16, v246
	v_and_b32_e32 v191, 0xffff0000, v246
	v_lshlrev_b32_e32 v192, 16, v247
	v_and_b32_e32 v193, 0xffff0000, v247
	v_lshlrev_b32_e32 v206, 16, v248
	v_and_b32_e32 v207, 0xffff0000, v248
	v_lshlrev_b32_e32 v208, 16, v249
	v_and_b32_e32 v209, 0xffff0000, v249
	v_pk_fma_f32 v[52:53], v[52:53], v[124:125], v[190:191]
	v_pk_fma_f32 v[54:55], v[54:55], v[126:127], v[192:193]
	v_pk_fma_f32 v[44:45], v[44:45], v[120:121], v[206:207]
	v_pk_fma_f32 v[46:47], v[46:47], v[122:123], v[208:209]
	v_cvt_pk_bf16_f32 v52, v52, v53
	v_cvt_pk_bf16_f32 v53, v54, v55
	v_cvt_pk_bf16_f32 v54, v44, v45
	v_cvt_pk_bf16_f32 v55, v46, v47
	global_store_dwordx4 v[188:189], v[52:55], off offset:256
	s_waitcnt vmcnt(15)
	v_lshlrev_b32_e32 v190, 16, v210
	v_and_b32_e32 v191, 0xffff0000, v210
	v_lshlrev_b32_e32 v192, 16, v211
	v_and_b32_e32 v193, 0xffff0000, v211
	v_lshlrev_b32_e32 v206, 16, v212
	v_and_b32_e32 v207, 0xffff0000, v212
	v_lshlrev_b32_e32 v208, 16, v213
	v_and_b32_e32 v209, 0xffff0000, v213
	v_lshl_add_u64 v[250:251], v[164:165], 0, v[180:181]
	v_pk_fma_f32 v[48:49], v[48:49], v[136:137], v[190:191]
	v_pk_fma_f32 v[50:51], v[50:51], v[138:139], v[192:193]
	v_pk_fma_f32 v[40:41], v[40:41], v[132:133], v[206:207]
	v_pk_fma_f32 v[42:43], v[42:43], v[134:135], v[208:209]
	v_cvt_pk_bf16_f32 v48, v48, v49
	v_cvt_pk_bf16_f32 v49, v50, v51
	v_cvt_pk_bf16_f32 v50, v40, v41
	v_cvt_pk_bf16_f32 v51, v42, v43
	global_store_dwordx4 v[250:251], v[48:51], off
	s_waitcnt vmcnt(14)
	v_lshlrev_b32_e32 v190, 16, v214
	v_and_b32_e32 v191, 0xffff0000, v214
	v_lshlrev_b32_e32 v192, 16, v215
	v_and_b32_e32 v193, 0xffff0000, v215
	v_lshlrev_b32_e32 v206, 16, v216
	v_and_b32_e32 v207, 0xffff0000, v216
	v_lshlrev_b32_e32 v208, 16, v217
	v_and_b32_e32 v209, 0xffff0000, v217
	v_pk_fma_f32 v[36:37], v[36:37], v[124:125], v[190:191]
	v_pk_fma_f32 v[38:39], v[38:39], v[126:127], v[192:193]
	v_pk_fma_f32 v[28:29], v[28:29], v[120:121], v[206:207]
	v_pk_fma_f32 v[30:31], v[30:31], v[122:123], v[208:209]
	v_cvt_pk_bf16_f32 v36, v36, v37
	v_cvt_pk_bf16_f32 v37, v38, v39
	v_cvt_pk_bf16_f32 v38, v28, v29
	v_cvt_pk_bf16_f32 v39, v30, v31
	global_store_dwordx4 v[250:251], v[36:39], off offset:256
	s_waitcnt vmcnt(13)
	v_lshlrev_b32_e32 v190, 16, v218
	v_and_b32_e32 v191, 0xffff0000, v218
	v_lshlrev_b32_e32 v192, 16, v219
	v_and_b32_e32 v193, 0xffff0000, v219
	v_lshlrev_b32_e32 v206, 16, v220
	v_and_b32_e32 v207, 0xffff0000, v220
	v_lshlrev_b32_e32 v208, 16, v221
	v_and_b32_e32 v209, 0xffff0000, v221
	v_lshl_add_u64 v[188:189], v[166:167], 0, v[180:181]
	v_pk_fma_f32 v[32:33], v[32:33], v[136:137], v[190:191]
	v_pk_fma_f32 v[34:35], v[34:35], v[138:139], v[192:193]
	v_pk_fma_f32 v[24:25], v[24:25], v[132:133], v[206:207]
	v_pk_fma_f32 v[26:27], v[26:27], v[134:135], v[208:209]
	v_cvt_pk_bf16_f32 v32, v32, v33
	v_cvt_pk_bf16_f32 v33, v34, v35
	v_cvt_pk_bf16_f32 v34, v24, v25
	v_cvt_pk_bf16_f32 v35, v26, v27
	global_store_dwordx4 v[188:189], v[32:35], off
	s_waitcnt vmcnt(12)
	v_lshlrev_b32_e32 v190, 16, v222
	v_and_b32_e32 v191, 0xffff0000, v222
	v_lshlrev_b32_e32 v192, 16, v223
	v_and_b32_e32 v193, 0xffff0000, v223
	v_lshlrev_b32_e32 v206, 16, v224
	v_and_b32_e32 v207, 0xffff0000, v224
	v_lshlrev_b32_e32 v208, 16, v225
	v_and_b32_e32 v209, 0xffff0000, v225
	v_pk_fma_f32 v[20:21], v[20:21], v[124:125], v[190:191]
	v_pk_fma_f32 v[22:23], v[22:23], v[126:127], v[192:193]
	v_pk_fma_f32 v[12:13], v[12:13], v[120:121], v[206:207]
	v_pk_fma_f32 v[14:15], v[14:15], v[122:123], v[208:209]
	v_cvt_pk_bf16_f32 v20, v20, v21
	v_cvt_pk_bf16_f32 v21, v22, v23
	v_cvt_pk_bf16_f32 v22, v12, v13
	v_cvt_pk_bf16_f32 v23, v14, v15
	global_store_dwordx4 v[188:189], v[20:23], off offset:256
	s_waitcnt vmcnt(11)
	v_lshlrev_b32_e32 v190, 16, v226
	v_and_b32_e32 v191, 0xffff0000, v226
	v_lshlrev_b32_e32 v192, 16, v227
	v_and_b32_e32 v193, 0xffff0000, v227
	v_lshlrev_b32_e32 v206, 16, v228
	v_and_b32_e32 v207, 0xffff0000, v228
	v_lshlrev_b32_e32 v208, 16, v229
	v_and_b32_e32 v209, 0xffff0000, v229
	v_lshl_add_u64 v[250:251], v[168:169], 0, v[180:181]
	v_pk_fma_f32 v[16:17], v[16:17], v[136:137], v[190:191]
	v_pk_fma_f32 v[18:19], v[18:19], v[138:139], v[192:193]
	v_pk_fma_f32 v[8:9], v[8:9], v[132:133], v[206:207]
	v_pk_fma_f32 v[10:11], v[10:11], v[134:135], v[208:209]
	v_cvt_pk_bf16_f32 v16, v16, v17
	v_cvt_pk_bf16_f32 v17, v18, v19
	v_cvt_pk_bf16_f32 v18, v8, v9
	v_cvt_pk_bf16_f32 v19, v10, v11
	global_store_dwordx4 v[250:251], v[16:19], off
	s_waitcnt vmcnt(10)
	v_lshlrev_b32_e32 v190, 16, v230
	v_and_b32_e32 v191, 0xffff0000, v230
	v_lshlrev_b32_e32 v192, 16, v231
	v_and_b32_e32 v193, 0xffff0000, v231
	v_lshlrev_b32_e32 v206, 16, v232
	v_and_b32_e32 v207, 0xffff0000, v232
	v_lshlrev_b32_e32 v208, 16, v233
	v_and_b32_e32 v209, 0xffff0000, v233
	v_pk_fma_f32 v[4:5], v[4:5], v[124:125], v[190:191]
	v_pk_fma_f32 v[6:7], v[6:7], v[126:127], v[192:193]
	v_pk_fma_f32 v[0:1], v[0:1], v[120:121], v[206:207]
	v_pk_fma_f32 v[2:3], v[2:3], v[122:123], v[208:209]
	v_cvt_pk_bf16_f32 v4, v4, v5
	v_cvt_pk_bf16_f32 v5, v6, v7
	v_cvt_pk_bf16_f32 v6, v0, v1
	v_cvt_pk_bf16_f32 v7, v2, v3
	global_store_dwordx4 v[250:251], v[4:7], off offset:256
.Lm2_epi_tail:
	s_mov_b32 s4, s0
	s_mov_b32 s5, s16
	s_and_b64 vcc, exec, s[38:39]
	s_mov_b64 s[22:23], s[14:15]
	s_mov_b64 s[20:21], s[24:25]
	s_cbranch_vccz .LBB0_833
	s_waitcnt vmcnt(0)
	s_cmpk_gt_u32 s42, 0xff
	s_cbranch_scc1 .LBB0_840
	s_barrier

	.amdhsa_kernel _Z10fwd_kernel4Args
		.amdhsa_group_segment_fixed_size 0
		.amdhsa_private_segment_fixed_size 0
		.amdhsa_kernarg_size 416
		.amdhsa_user_sgpr_count 2
		.amdhsa_user_sgpr_dispatch_ptr 0
		.amdhsa_user_sgpr_queue_ptr 0
		.amdhsa_user_sgpr_kernarg_segment_ptr 1
		.amdhsa_user_sgpr_dispatch_id 0
		.amdhsa_user_sgpr_kernarg_preload_length 0
		.amdhsa_user_sgpr_kernarg_preload_offset 0
		.amdhsa_user_sgpr_private_segment_size 0
		.amdhsa_uses_dynamic_stack 0
		.amdhsa_enable_private_segment 0
		.amdhsa_system_sgpr_workgroup_id_x 1
		.amdhsa_system_sgpr_workgroup_id_y 0
		.amdhsa_system_sgpr_workgroup_id_z 0
		.amdhsa_system_sgpr_workgroup_info 0
		.amdhsa_system_vgpr_workitem_id 2
		.amdhsa_next_free_vgpr 254
		.amdhsa_next_free_sgpr 102
		.amdhsa_accum_offset 256
		.amdhsa_reserve_vcc 1
		.amdhsa_float_round_mode_32 0
		.amdhsa_float_round_mode_16_64 0
		.amdhsa_float_denorm_mode_32 3
		.amdhsa_float_denorm_mode_16_64 3
		.amdhsa_dx10_clamp 1
		.amdhsa_ieee_mode 1
		.amdhsa_fp16_overflow 0
		.amdhsa_tg_split 0
		.amdhsa_exception_fp_ieee_invalid_op 0
		.amdhsa_exception_fp_denorm_src 0
		.amdhsa_exception_fp_ieee_div_zero 0
		.amdhsa_exception_fp_ieee_overflow 0
		.amdhsa_exception_fp_ieee_underflow 0
		.amdhsa_exception_fp_ieee_inexact 0
		.amdhsa_exception_int_div_zero 0
	.end_amdhsa_kernel

.Lfunc_end0:
	.size	_Z10fwd_kernel4Args, .Lfunc_end0-_Z10fwd_kernel4Args
	.set _Z10fwd_kernel4Args.num_vgpr, 254
	.set _Z10fwd_kernel4Args.num_agpr, 0
	.set _Z10fwd_kernel4Args.numbered_sgpr, 102
	.set _Z10fwd_kernel4Args.num_named_barrier, 0
	.set _Z10fwd_kernel4Args.private_seg_size, 0
	.set _Z10fwd_kernel4Args.uses_vcc, 1
	.set _Z10fwd_kernel4Args.uses_flat_scratch, 0
	.set _Z10fwd_kernel4Args.has_dyn_sized_stack, 0
	.set _Z10fwd_kernel4Args.has_recursion, 0
	.set _Z10fwd_kernel4Args.has_indirect_call, 0

amdhsa.kernels:
  - .agpr_count:     0
    .args:
      - .offset:         0
        .size:           160
        .value_kind:     by_value
      - .offset:         160
        .size:           4
        .value_kind:     hidden_block_count_x
      - .offset:         164
        .size:           4
        .value_kind:     hidden_block_count_y
      - .offset:         168
        .size:           4
        .value_kind:     hidden_block_count_z
      - .offset:         172
        .size:           2
        .value_kind:     hidden_group_size_x
      - .offset:         174
        .size:           2
        .value_kind:     hidden_group_size_y
      - .offset:         176
        .size:           2
        .value_kind:     hidden_group_size_z
      - .offset:         178
        .size:           2
        .value_kind:     hidden_remainder_x
      - .offset:         180
        .size:           2
        .value_kind:     hidden_remainder_y
      - .offset:         182
        .size:           2
        .value_kind:     hidden_remainder_z
      - .offset:         200
        .size:           8
        .value_kind:     hidden_global_offset_x
      - .offset:         208
        .size:           8
        .value_kind:     hidden_global_offset_y
      - .offset:         216
        .size:           8
        .value_kind:     hidden_global_offset_z
      - .offset:         224
        .size:           2
        .value_kind:     hidden_grid_dims
      - .offset:         248
        .size:           8
        .value_kind:     hidden_multigrid_sync_arg
      - .offset:         280
        .size:           4
        .value_kind:     hidden_dynamic_lds_size
    .group_segment_fixed_size: 0
    .kernarg_segment_align: 8
    .kernarg_segment_size: 416
    .language:       OpenCL C
    .language_version:
      - 2
      - 0
    .max_flat_workgroup_size: 512
    .name:           _Z10fwd_kernel4Args
    .private_segment_fixed_size: 0
    .sgpr_count:     108
    .sgpr_spill_count: 127
    .symbol:         _Z10fwd_kernel4Args.kd
    .uniform_work_group_size: 1
    .uses_dynamic_stack: false
    .vgpr_count:     254
    .vgpr_spill_count: 0
    .wavefront_size: 64
